# A->B seam as 8-workgroup arrive/wait, placement check generalized to any residue->XCC permutation (group path active)
# baseline (speedup 1.0000x reference)
_Z10fwd_kernel6Params:
	s_load_dwordx8 s[36:43], s[0:1], 0x40
	s_load_dword s3, s[0:1], 0x60
	s_add_u32 s6, s0, 0x58
	v_and_b32_e32 v1, 0x3ff, v0
	s_addc_u32 s7, s1, 0
	v_cmp_gt_u32_e32 vcc, 16, v1
	s_and_saveexec_b64 s[4:5], vcc
	v_lshl_add_u32 v2, v1, 2, 0
	v_add_u32_e32 v2, 0x23fc0, v2
	v_mov_b32_e32 v3, 0
	ds_write_b32 v2, v3
	s_or_b64 exec, exec, s[4:5]
	s_waitcnt lgkmcnt(0)
	s_add_u32 s96, s40, 0x4000
	s_barrier
	s_addc_u32 s97, s41, 0
	s_getreg_b32 s10, hwreg(HW_REG_XCC_ID, 0, 4)
	v_cmp_eq_u32_e64 s[64:65], 0, v1
	s_and_saveexec_b64 s[4:5], s[64:65]
	s_cbranch_execz .LBB0_5
	s_mov_b64 s[8:9], exec
	v_mbcnt_lo_u32_b32 v2, s8, 0
	v_mbcnt_hi_u32_b32 v2, s9, v2
	v_cmp_eq_u32_e32 vcc, 0, v2
	s_and_b64 s[12:13], exec, vcc
	s_mov_b64 exec, s[12:13]
	s_cbranch_execz .LBB0_5
	s_and_b32 s11, s2, 7
	s_lshl_b32 s11, s11, 2
	s_and_b32 s14, s10, 15
	s_lshl_b32 s14, 1, s14
	v_mov_b32_e32 v2, s11
	v_mov_b32_e32 v3, s14
	global_atomic_or v2, v3, s[96:97] offset:256
	s_lshl_b32 s10, s10, 8
	s_and_b32 s10, s10, 0xf00
	s_bcnt1_i32_b64 s8, s[8:9]
	v_mov_b32_e32 v2, s10
	v_mov_b32_e32 v3, s8
	global_atomic_add v2, v3, s[96:97] offset:1024

.LBB0_127:
	s_lshr_b32 s1, s42, 3
	s_mul_i32 s1, s1, s4
	s_and_b32 s0, s42, 7
	s_add_i32 s1, s1, s5
	s_lshl_b32 s5, s51, 7
	s_cmp_eq_u32 s0, 0
	s_cselect_b32 s66, s1, s2
	s_mul_hi_i32 s6, s66, 0x2aaaaaab
	s_ashr_i32 s10, s6, 7
	s_lshr_b32 s7, s6, 31
	s_add_i32 s10, s10, s7
	s_mul_i32 s0, s10, 0x300
	s_sub_i32 s9, s66, s0
	s_mul_i32 s0, s9, 0x2aab
	s_lshr_b32 s1, s0, 31
	s_ashr_i32 s0, s0, 19
	s_add_i32 s0, s0, s1
	s_mul_i32 s1, s0, 48
	s_sub_i32 s1, s9, s1
	s_sext_i32_i16 s1, s1
	s_add_i32 s8, s66, 0x2ff
	s_and_b32 s12, s1, 7
	s_and_b32 s11, s1, 1
	s_cmp_lt_i32 s51, 0
	s_mul_i32 s13, s51, 0x81
	s_movk_i32 s67, 0x1c1
	s_cselect_b32 s4, s67, 0x1c0
	s_cselect_b32 s5, s13, s5
	s_cmpk_lt_u32 s8, 0x5ff
	s_cselect_b32 s14, s11, s12
	s_bfe_u32 s11, s1, 0x20001
	s_sext_i32_i16 s13, s9
	s_cmpk_lt_u32 s8, 0x5ff
	s_mul_i32 s15, s13, 0x2aab
	s_cselect_b32 s13, s11, 0
	s_lshr_b32 s11, s15, 31
	s_ashr_i32 s15, s15, 19
	s_add_i32 s15, s15, s11
	s_mul_i32 s11, s15, 48
	s_sub_i32 s9, s9, s11
	s_sext_i32_i16 s11, s9
	s_and_b32 s16, s11, 7
	s_and_b32 s9, s11, 1
	s_cmpk_lt_u32 s8, 0x5ff
	s_cselect_b32 s17, s9, s16
	s_bfe_u32 s9, s11, 0x20001
	s_cmpk_lt_u32 s8, 0x5ff
	s_mulk_i32 s9, 0x3800
	s_cselect_b32 s9, s9, 0
	s_cmpk_lt_i32 s2, 0xe00
	s_cselect_b64 s[18:19], -1, 0
	s_add_u32 s72, s40, 0x4200
	s_addc_u32 s73, s41, 0
	s_add_u32 s74, s40, 0x4400
	s_addc_u32 s75, s41, 0
	s_add_u32 s76, s40, 0x4500
	s_addc_u32 s77, s41, 0
	s_add_u32 s90, s40, 0x4600
	s_addc_u32 s91, s41, 0
	s_add_u32 s26, s40, 0x4700
	s_mul_i32 s8, s43, s42
	v_writelane_b32 v252, s9, 21
	s_addc_u32 s27, s41, 0
	v_writelane_b32 v252, s18, 22
	s_mul_i32 s70, s8, s3
	s_add_u32 s8, s40, 0x4800
	v_writelane_b32 v252, s19, 23
	s_addc_u32 s9, s41, 0
	v_writelane_b32 v252, s8, 24
	s_mul_i32 s4, s51, s4
	s_mov_b32 s99, 0
	v_writelane_b32 v252, s9, 25
	s_add_u32 s8, s40, 0x4900
	s_addc_u32 s9, s41, 0
	v_writelane_b32 v252, s8, 26
	s_mov_b32 s44, 0xe000
	s_movk_i32 s47, 0x800
	v_writelane_b32 v252, s9, 27
	s_add_u32 s8, s40, 0x4a00
	s_addc_u32 s9, s41, 0
	v_writelane_b32 v252, s8, 28
	s_movk_i32 s83, 0x200
	s_movk_i32 s33, 0x81
	v_writelane_b32 v252, s9, 29
	s_add_u32 s8, s40, 0x4b00
	s_addc_u32 s9, s41, 0
	v_writelane_b32 v252, s8, 30
	s_movk_i32 s43, 0x3800
	s_movk_i32 s94, 0x600
	v_writelane_b32 v252, s9, 31
	s_add_u32 s8, s40, 0x4c00
	s_addc_u32 s9, s41, 0
	v_writelane_b32 v252, s8, 32
	v_mov_b32_e32 v1, 0
	v_mov_b32_e32 v205, 0x2000
	v_writelane_b32 v252, s9, 33
	s_add_u32 s8, s40, 0x4d00
	s_addc_u32 s9, s41, 0
	v_writelane_b32 v252, s8, 34
	v_mov_b32_e32 v206, 1
	s_mov_b64 s[92:93], 0x600
	v_writelane_b32 v252, s9, 35
	s_add_u32 s8, s40, 0x4e00
	s_addc_u32 s9, s41, 0
	v_writelane_b32 v252, s8, 36
	v_mbcnt_hi_u32_b32 v207, -1, v146
	v_mov_b32_e32 v208, 0x358637bd
	v_writelane_b32 v252, s9, 37
	s_add_u32 s8, s40, 0x4f00
	s_addc_u32 s9, s41, 0
	v_writelane_b32 v252, s8, 38
	v_mov_b32_e32 v209, 0x260
	v_mov_b64_e32 v[148:149], 0xe00
	v_writelane_b32 v252, s9, 39
	s_add_u32 s8, s40, 0x5000
	s_addc_u32 s9, s41, 0
	v_writelane_b32 v252, s8, 40
	v_mov_b64_e32 v[150:151], 0xdff
	v_mov_b32_e32 v210, 0xf149f2ca
	v_writelane_b32 v252, s9, 41
	s_add_u32 s8, s40, 0x5100
	s_addc_u32 s9, s41, 0
	v_writelane_b32 v252, s8, 42
	v_mov_b32_e32 v211, 0x3800
	v_mov_b32_e32 v212, 0x400
	v_writelane_b32 v252, s9, 43
	s_add_u32 s8, s40, 0x5200
	s_addc_u32 s9, s41, 0
	v_writelane_b32 v252, s8, 44
	v_mov_b32_e32 v213, 0x7e0
	v_mov_b32_e32 v214, 0x600
	v_writelane_b32 v252, s9, 45
	s_add_u32 s8, s40, 0x5300
	s_addc_u32 s9, s41, 0
	v_writelane_b32 v252, s8, 46
	v_mov_b64_e32 v[152:153], 0x400
	v_mov_b64_e32 v[154:155], 0x3ff
	v_writelane_b32 v252, s9, 47
	s_add_u32 s8, s40, 0x7400
	s_addc_u32 s9, s41, 0
	v_writelane_b32 v252, s8, 48
	s_nop 1
	v_writelane_b32 v252, s9, 49
	s_add_u32 s8, s40, 0x7500
	s_addc_u32 s9, s41, 0
	v_writelane_b32 v252, s8, 50
	s_lshl_b32 s3, s95, 2
	s_lshl_b32 s31, s95, 5
	v_writelane_b32 v252, s9, 51
	v_writelane_b32 v252, s3, 52
	s_lshl_b32 s3, s95, 1
	s_and_b32 s29, s3, 2
	s_lshl_b32 s3, s95, 10
	s_add_i32 s85, s3, 0
	s_add_i32 s30, s85, s3
	s_add_i32 s3, s85, 0x2000
	v_writelane_b32 v252, s3, 53
	s_add_i32 s3, s30, 0x400
	v_writelane_b32 v252, s3, 54
	s_add_i32 s3, s85, 0x4000
	v_writelane_b32 v252, s3, 55
	s_add_i32 s3, s85, 0x6000
	v_writelane_b32 v252, s3, 56
	s_add_i32 s3, s30, 0x4000
	v_writelane_b32 v252, s3, 57
	s_add_i32 s3, s30, 0x4400
	v_writelane_b32 v252, s3, 58
	s_add_i32 s3, s85, 0x8000
	v_writelane_b32 v252, s3, 59
	s_add_i32 s3, s85, 0xa000
	v_writelane_b32 v252, s3, 60
	s_add_i32 s3, s30, 0x8000
	v_writelane_b32 v252, s3, 61
	s_add_i32 s3, s30, 0x8400
	v_writelane_b32 v252, s3, 62
	s_add_i32 s3, s85, 0xc000
	v_writelane_b32 v252, s3, 63
	s_add_i32 s3, s85, 0xe000
	v_writelane_b32 v253, s3, 0
	s_add_i32 s3, s30, 0xc000
	v_writelane_b32 v253, s3, 1
	s_add_i32 s3, s30, 0xc400
	v_writelane_b32 v253, s3, 2
	s_and_b32 s3, s31, 0x60
	v_writelane_b32 v253, s3, 3
	s_mul_i32 s3, s95, 0x1200
	s_add_i32 s3, s3, 0
	s_add_i32 s3, s3, 0x1ae00
	v_writelane_b32 v253, s3, 4
	s_lshl_b32 s3, s95, 9
	s_lshr_b32 s8, s34, 8
	s_and_b32 s3, s3, 0x600
	v_writelane_b32 v253, s8, 5
	s_add_i32 s3, s3, s8
	s_bfe_u32 s84, s34, 0x20006
	s_lshl_b32 s28, s95, 3
	v_writelane_b32 v253, s3, 6
	s_add_i32 s3, s95, 4
	s_cmpk_lt_i32 s2, 0x400
	s_cselect_b64 s[8:9], -1, 0
	v_writelane_b32 v253, s8, 7
	s_add_i32 s4, s4, s50
	s_ashr_i32 s6, s6, 3
	v_writelane_b32 v253, s9, 8
	s_mul_hi_i32 s8, s4, 0x92492493
	s_add_i32 s8, s8, s4
	s_lshr_b32 s9, s8, 31
	s_ashr_i32 s8, s8, 7
	s_add_i32 s8, s8, s9
	s_mul_i32 s9, s8, 0xe0
	s_sub_i32 s9, s4, s9
	s_bfe_u32 s4, s9, 0x3001c
	s_add_i32 s18, s9, s4
	s_sext_i32_i16 s19, s18
	s_and_b32 s18, s18, 0xfff8
	s_sub_i32 s9, s9, s18
	s_lshl_b32 s8, s8, 3
	s_sext_i32_i16 s9, s9
	s_add_i32 s46, s8, s9
	s_ashr_i32 s8, s19, 3
	v_writelane_b32 v253, s8, 9
	s_ashr_i32 s8, s66, 3
	s_mul_hi_i32 s9, s8, 0x55555556
	s_lshr_b32 s18, s9, 31
	s_add_i32 s9, s9, s18
	s_mul_i32 s9, s9, 3
	s_sub_i32 s82, s8, s9
	s_ashr_i32 s8, s66, 5
	s_add_i32 s6, s6, s7
	s_ashr_i32 s9, s8, 31
	s_mul_i32 s7, s6, 48
	s_lshr_b32 s4, s19, 3
	s_lshl_b64 s[18:19], s[8:9], 21
	s_sub_i32 s20, s66, s7
	v_writelane_b32 v253, s18, 10
	s_lshl_b32 s7, s20, 2
	s_lshl_b32 s48, s42, 4
	v_writelane_b32 v253, s19, 11
	s_lshl_b32 s18, s66, 5
	s_and_b32 s19, s7, 28
	s_and_b32 s18, s18, 0x300
	v_sub_u32_e64 v0, s19, 1 clamp
	v_writelane_b32 v253, s18, 12
	v_readfirstlane_b32 s18, v0
	s_max_u32 s7, s19, 4
	s_min_u32 s18, s18, 24
	s_sub_i32 s18, s18, s7
	s_lshl_b32 s18, s18, 1
	s_add_i32 s18, s18, 24
	s_lshl_b32 s7, s7, 6
	v_writelane_b32 v253, s18, 13
	s_add_i32 s18, s7, 0xffffff00
	s_ashr_i32 s7, s6, 31
	s_lshl_b64 s[24:25], s[6:7], 11
	s_add_u32 s7, s24, s18
	v_writelane_b32 v253, s24, 14
	s_addc_u32 s18, s25, 0
	s_mul_hi_u32 s21, s7, 0x3800
	s_mulk_i32 s18, 0x3800
	v_writelane_b32 v253, s25, 15
	s_add_i32 s18, s21, s18
	v_writelane_b32 v253, s18, 16
	s_lshl_b32 s18, s20, 4
	s_and_b32 s45, s18, 0xffffff80
	s_add_i32 s98, s45, 0x300
	s_lshl_b32 s11, s11, 4
	s_lshl_b64 s[24:25], s[98:99], 1
	s_and_b32 s11, s11, 0xffffff80
	v_writelane_b32 v253, s24, 17
	s_add_i32 s98, s11, 0xf00
	v_add_co_u32_e64 v0, s[10:11], s10, 1
	v_writelane_b32 v253, s25, 18
	s_lshl_b64 s[24:25], s[98:99], 1
	v_writelane_b32 v253, s24, 19
	s_lshl_b32 s17, s17, 8
	v_cmp_ne_u32_e64 s[52:53], 2, v0
	v_writelane_b32 v253, s25, 20
	s_and_b64 s[24:25], s[10:11], exec
	v_writelane_b32 v253, s17, 21
	s_cselect_b32 s17, s47, 0x200
	s_cselect_b32 s24, 0x3800, s44
	s_add_i32 s18, s66, s42
	v_writelane_b32 v253, s17, 22
	s_cmp_eq_u32 s82, 1
	s_cselect_b32 s17, 1, 2
	s_cselect_b32 s21, s83, 0x600
	v_writelane_b32 v253, s52, 23
	s_cmp_eq_u32 s82, 0
	s_cselect_b32 s17, 0, s17
	v_writelane_b32 v253, s53, 24
	v_writelane_b32 v253, s17, 25
	s_mulk_i32 s7, 0x3800
	v_writelane_b32 v253, s7, 26
	s_mul_hi_i32 s7, s15, 0x1c00000
	v_writelane_b32 v253, s7, 27
	s_mul_i32 s7, s15, 0x1c00000
	v_writelane_b32 v253, s7, 28
	s_mov_b32 s25, s99
	v_writelane_b32 v253, s24, 29
	s_mul_i32 s7, s16, 0x7000
	s_nop 0
	v_writelane_b32 v253, s25, 30
	v_writelane_b32 v253, s7, 31
	s_cselect_b32 s7, 0x300, s21
	s_cmp_ge_i32 s18, s7
	s_cselect_b64 s[16:17], -1, 0
	s_and_b64 s[24:25], s[16:17], exec
	v_cndmask_b32_e64 v0, 0, 1, s[16:17]
	s_cselect_b32 s24, s66, s18
	v_readfirstlane_b32 s7, v0
	s_cmp_lg_u64 s[16:17], 0
	s_nop 0
	v_writelane_b32 v253, s7, 32
	s_addc_u32 s7, s82, 0
	s_cmp_lg_u64 s[16:17], 0
	s_addc_u32 s15, s82, -3
	s_cmp_gt_i32 s7, 2
	s_cselect_b32 s7, s15, s7
	s_cmp_eq_u32 s7, 1
	s_cselect_b32 s15, 1, 2
	s_cmp_lg_u32 s7, 0
	s_cselect_b32 s7, s15, 0
	s_ashr_i32 s16, s24, 5
	s_ashr_i32 s17, s16, 31
	v_writelane_b32 v253, s7, 33
	s_lshl_b64 s[16:17], s[16:17], 21
	v_writelane_b32 v253, s16, 34
	s_lshl_b32 s7, s24, 5
	s_and_b32 s7, s7, 0x300
	v_writelane_b32 v253, s17, 35
	v_writelane_b32 v253, s7, 36
	s_mul_hi_i32 s7, s24, 0x2aaaaaab
	s_ashr_i32 s15, s7, 3
	s_lshr_b32 s18, s7, 31
	s_add_i32 s16, s15, s18
	s_mul_i32 s15, s16, 48
	s_sub_i32 s15, s24, s15
	s_lshl_b32 s17, s15, 2
	s_and_b32 s17, s17, 28
	v_sub_u32_e64 v0, s17, 1 clamp
	s_max_u32 s21, s17, 4
	v_readfirstlane_b32 s17, v0
	s_min_u32 s17, s17, 24
	s_sub_i32 s17, s17, s21
	s_lshl_b32 s17, s17, 1
	s_add_i32 s17, s17, 24
	v_writelane_b32 v253, s17, 37
	s_ashr_i32 s17, s16, 31
	s_lshl_b32 s21, s21, 6
	s_lshl_b64 s[16:17], s[16:17], 11
	s_addk_i32 s21, 0xff00
	s_add_u32 s16, s16, s21
	s_addc_u32 s17, s17, 0
	s_mul_hi_u32 s21, s16, 0x3800
	s_mulk_i32 s17, 0x3800
	s_lshl_b32 s15, s15, 4
	s_add_i32 s17, s21, s17
	s_and_b32 s15, s15, 0xffffff80
	v_writelane_b32 v253, s17, 38
	s_mulk_i32 s16, 0x3800
	s_add_i32 s98, s15, 0x300
	v_writelane_b32 v253, s16, 39
	s_lshl_b64 s[16:17], s[98:99], 1
	s_ashr_i32 s7, s7, 7
	v_writelane_b32 v253, s16, 40
	s_add_i32 s7, s7, s18
	s_nop 0
	v_writelane_b32 v253, s17, 41
	v_add_co_u32_e64 v0, s[16:17], s7, 1
	s_mulk_i32 s7, 0x300
	s_sub_i32 s7, s24, s7
	s_mul_i32 s15, s7, 0x2aab
	s_lshr_b32 s18, s15, 31
	s_ashr_i32 s15, s15, 19
	s_add_i32 s15, s15, s18
	s_mul_i32 s18, s15, 48
	s_sub_i32 s7, s7, s18
	s_sext_i32_i16 s7, s7
	s_mul_hi_i32 s18, s15, 0x1c00000
	v_writelane_b32 v253, s18, 42
	s_lshl_b32 s18, s7, 4
	s_and_b32 s18, s18, 0xffffff80
	s_mul_i32 s15, s15, 0x1c00000
	s_add_i32 s98, s18, 0xf00
	v_writelane_b32 v253, s15, 43
	s_lshl_b64 s[52:53], s[98:99], 1
	v_writelane_b32 v253, s52, 44
	s_and_b32 s15, s7, 7
	s_add_i32 s18, s24, 0x2ff
	v_writelane_b32 v253, s53, 45
	v_cmp_ne_u32_e64 s[52:53], 2, v0
	s_bfe_u32 s21, s7, 0x20001
	s_and_b32 s7, s7, 1
	v_writelane_b32 v253, s52, 46
	s_cmpk_lt_u32 s18, 0x5ff
	s_mulk_i32 s21, 0x3800
	v_writelane_b32 v253, s53, 47
	s_cselect_b32 s7, s7, s15
	v_writelane_b32 v253, s24, 48
	s_cselect_b32 s18, s21, 0
	s_lshl_b32 s7, s7, 8
	v_writelane_b32 v253, s18, 49
	s_and_b64 s[16:17], s[16:17], exec
	v_writelane_b32 v253, s7, 50
	s_cselect_b32 s7, s47, 0x200
	v_writelane_b32 v253, s7, 51
	s_cselect_b32 s16, 0x3800, s44
	s_mov_b32 s17, s99
	v_writelane_b32 v253, s16, 52
	s_mul_i32 s7, s15, 0x7000
	s_lshl_b64 s[8:9], s[8:9], 11
	v_writelane_b32 v253, s17, 53
	v_writelane_b32 v253, s7, 54
	v_writelane_b32 v253, s8, 55
	s_lshl_b32 s7, s66, 8
	s_and_b32 s7, s7, 0x700
	v_writelane_b32 v253, s9, 56
	v_writelane_b32 v253, s7, 57
	s_lshl_b32 s7, s66, 4
	s_and_b32 s7, s7, 0x180
	s_or_b32 s7, s7, 0x1800
	s_lshl_b32 s1, s1, 4
	v_writelane_b32 v253, s7, 58
	s_and_b32 s1, s1, 0xffffff80
	v_writelane_b32 v253, s28, 59
	s_addk_i32 s1, 0xc00
	v_writelane_b32 v253, s1, 60
	s_ashr_i32 s1, s0, 31
	s_lshl_b64 s[8:9], s[0:1], 11
	s_lshl_b32 s0, s14, 8
	s_and_b32 s7, s28, 0x1ffffff0
	s_add_i32 s0, s0, s31
	v_writelane_b32 v253, s0, 61
	s_and_b64 s[0:1], s[10:11], exec
	s_cselect_b32 s0, 0, 2
	v_writelane_b32 v253, s0, 62
	s_or_b32 s0, s8, s13
	s_mov_b32 s1, s9
	v_writelane_b32 v253, s0, 63
	v_sub_u32_e64 v0, s7, 8 clamp
	s_add_i32 s98, s45, 0xf00
	v_writelane_b32 v254, s1, 0
	s_lshl_b32 s0, s12, 1
	s_or_b32 s8, s8, s0
	v_writelane_b32 v254, s8, 1
	v_readfirstlane_b32 s0, v0
	s_min_u32 s18, s0, 32
	v_writelane_b32 v254, s9, 2
	v_writelane_b32 v254, s7, 3
	s_mul_hi_i32 s0, s6, 0x1c00000
	v_writelane_b32 v254, s0, 4
	s_mul_i32 s0, s6, 0x1c00000
	v_writelane_b32 v254, s0, 5
	s_lshl_b64 s[0:1], s[98:99], 1
	v_writelane_b32 v254, s0, 6
	s_add_i32 s98, s45, 0xc00
	s_ashr_i32 s47, s46, 31
	v_writelane_b32 v254, s1, 7
	s_lshl_b32 s0, s20, 8
	s_and_b32 s1, s0, 0x700
	s_max_u32 s0, s1, 64
	s_mulk_i32 s0, 0x3800
	v_writelane_b32 v254, s0, 8
	s_max_u32 s0, s1, 32
	s_mulk_i32 s0, 0x3800
	v_writelane_b32 v254, s0, 9
	v_writelane_b32 v254, s45, 10
	v_writelane_b32 v254, s1, 11
	s_add_i32 s0, s1, s31
	v_writelane_b32 v254, s0, 12
	s_lshl_b64 s[0:1], s[98:99], 1
	v_writelane_b32 v254, s0, 13
	s_ashr_i32 s81, s80, 31
	s_mov_b64 s[44:45], 0x80
	v_writelane_b32 v254, s1, 14
	s_add_i32 s0, s5, s50
	s_ashr_i32 s1, s0, 31
	s_lshr_b32 s1, s1, 26
	s_add_i32 s1, s0, s1
	s_ashr_i32 s5, s1, 6
	s_and_b32 s1, s1, 0xffc0
	s_sub_i32 s1, s0, s1
	s_bfe_i32 s0, s1, 0x80000
	s_bfe_u32 s0, s0, 0x3000c
	s_add_i32 s6, s1, s0
	s_bfe_i32 s0, s6, 0x80000
	s_and_b32 s6, s6, 0xf8
	s_sub_i32 s1, s1, s6
	s_lshl_b32 s5, s5, 3
	s_sext_i32_i16 s7, s0
	s_sext_i32_i8 s1, s1
	s_add_i32 s8, s5, s1
	s_ashr_i32 s1, s7, 3
	v_writelane_b32 v254, s1, 15
	s_mov_b32 s6, s8
	s_lshr_b32 s0, s7, 3
	s_ashr_i32 s9, s8, 31
	v_writelane_b32 v254, s6, 16
	s_bfe_i64 s[0:1], s[0:1], 0x100000
	s_lshl_b64 s[0:1], s[0:1], 20
	v_writelane_b32 v254, s7, 17
	s_lshl_b64 s[6:7], s[8:9], 20
	v_writelane_b32 v254, s6, 18
	s_nop 1
	v_writelane_b32 v254, s7, 19
	v_writelane_b32 v254, s0, 20
	s_nop 1
	v_writelane_b32 v254, s1, 21
	s_mov_b32 s0, s46
	v_writelane_b32 v254, s0, 22
	s_nop 1
	v_writelane_b32 v254, s1, 23
	s_lshl_b64 s[0:1], s[46:47], 20
	v_writelane_b32 v254, s0, 24
	s_sub_i32 s46, 0, s95
	s_mov_b32 s47, 0xc0000
	v_writelane_b32 v254, s1, 25
	s_bfe_i64 s[0:1], s[4:5], 0x100000
	s_lshl_b64 s[0:1], s[0:1], 20
	v_writelane_b32 v254, s0, 26
	s_nop 1
	v_writelane_b32 v254, s1, 27
	v_writelane_b32 v254, s29, 28
	s_or_b32 s0, s19, s29
	s_lshr_b32 s1, s34, 1
	v_writelane_b32 v254, s0, 29
	s_lshl_b32 s0, s18, 2
	s_and_b32 s1, s1, 0x7fffffc0
	s_sub_i32 s0, s0, s1
	s_bfe_u32 s1, s34, 0x10006
	s_mulk_i32 s1, 0xf8
	s_sub_i32 s0, s0, s1
	s_add_i32 s0, s0, 0
	s_add_i32 s0, s0, 0x182b0
	v_writelane_b32 v254, s0, 30
	s_sub_i32 s0, -2, s95
	v_writelane_b32 v254, s0, 31
	s_sub_i32 s0, 0, s31
	v_writelane_b32 v254, s0, 32
	s_lshl_b64 s[0:1], s[80:81], 12
	s_add_u32 s4, s0, 0x13400000
	v_writelane_b32 v254, s4, 33
	s_addc_u32 s4, s1, 0
	v_writelane_b32 v254, s4, 34
	s_ashr_i32 s49, s48, 31
	v_writelane_b32 v254, s48, 35
	s_lshl_b64 s[4:5], s[48:49], 12
	s_mov_b32 s19, 0
	v_writelane_b32 v254, s49, 36
	v_writelane_b32 v254, s4, 37
	s_nop 1
	v_writelane_b32 v254, s5, 38
	s_mov_b32 s4, s80
	v_writelane_b32 v254, s4, 39
	s_nop 1
	v_writelane_b32 v254, s5, 40
	s_lshl_b64 s[4:5], s[80:81], 13
	s_add_u32 s6, s38, s4
	v_writelane_b32 v254, s4, 41
	s_addc_u32 s7, s39, s5
	s_lshl_b64 s[78:79], s[48:49], 13
	v_writelane_b32 v254, s5, 42
	s_add_u32 s0, s0, 0x1b400000
	v_writelane_b32 v254, s0, 43
	s_addc_u32 s0, s1, 0
	v_writelane_b32 v254, s0, 44
	s_add_u32 s0, s6, 0x1000
	v_writelane_b32 v254, s6, 45
	s_addc_u32 s1, s7, 0
	v_readlane_b32 s48, v252, 0
	v_writelane_b32 v254, s7, 46
	v_writelane_b32 v254, s0, 47
	v_readlane_b32 s56, v252, 8
	v_readlane_b32 s57, v252, 9
	v_writelane_b32 v254, s1, 48
	s_add_i32 s0, 0, 0x23fc0
	v_writelane_b32 v254, s0, 49
	s_add_i32 s0, 0, 0x23fc4
	v_writelane_b32 v254, s0, 50
	s_add_i32 s0, 0, 0x18100
	v_writelane_b32 v254, s0, 51
	s_add_i32 s0, 0, 0x18900
	v_writelane_b32 v254, s0, 52
	s_mov_b64 s[0:1], s[56:57]
	v_writelane_b32 v254, s0, 53
	s_mov_b64 s[56:57], s[26:27]
	v_readlane_b32 s49, v252, 1
	v_writelane_b32 v254, s1, 54
	v_writelane_b32 v254, s72, 55
	v_readlane_b32 s50, v252, 2
	v_readlane_b32 s51, v252, 3
	v_writelane_b32 v254, s73, 56
	v_writelane_b32 v254, s74, 57
	v_readlane_b32 s52, v252, 4
	v_readlane_b32 s53, v252, 5
	v_writelane_b32 v254, s75, 58
	v_writelane_b32 v254, s76, 59
	v_readlane_b32 s54, v252, 6
	v_readlane_b32 s55, v252, 7
	v_writelane_b32 v254, s77, 60
	v_writelane_b32 v254, s90, 61
	v_readlane_b32 s58, v252, 10
	v_readlane_b32 s59, v252, 11
	v_writelane_b32 v254, s91, 62
	v_writelane_b32 v254, s56, 63
	v_readlane_b32 s60, v252, 12
	v_readlane_b32 s61, v252, 13
	v_writelane_b32 v255, s57, 0
	v_writelane_b32 v255, s96, 1
	v_readlane_b32 s62, v252, 14
	v_readlane_b32 s63, v252, 15
	v_writelane_b32 v255, s97, 2
	v_writelane_b32 v255, s68, 3
	s_nop 1
	v_writelane_b32 v255, s69, 4
	v_writelane_b32 v255, s70, 5
	v_readlane_b32 s0, v255, 1
	v_readlane_b32 s1, v255, 2
	v_mov_b32_e32 v0, 0
	s_nop 4
	global_load_dwordx4 v[2:5], v0, s[0:1] offset:256 sc1
	global_load_dwordx4 v[6:9], v0, s[0:1] offset:272 sc1
	s_waitcnt vmcnt(0)
	v_bcnt_u32_b32 v2, v2, 0
	v_bcnt_u32_b32 v3, v3, 0
	v_bcnt_u32_b32 v4, v4, 0
	v_bcnt_u32_b32 v5, v5, 0
	v_bcnt_u32_b32 v6, v6, 0
	v_bcnt_u32_b32 v7, v7, 0
	v_bcnt_u32_b32 v8, v8, 0
	v_bcnt_u32_b32 v9, v9, 0
	v_xor_b32_e32 v2, 1, v2
	v_xor_b32_e32 v3, 1, v3
	v_xor_b32_e32 v4, 1, v4
	v_xor_b32_e32 v5, 1, v5
	v_xor_b32_e32 v6, 1, v6
	v_xor_b32_e32 v7, 1, v7
	v_xor_b32_e32 v8, 1, v8
	v_xor_b32_e32 v9, 1, v9
	v_or3_b32 v2, v2, v3, v4
	v_or3_b32 v5, v5, v6, v7
	v_or3_b32 v2, v2, v8, v9
	v_or_b32_e32 v2, v2, v5
	s_nop 0
	v_readfirstlane_b32 s0, v2
	s_nop 3
	v_writelane_b32 v255, s0, 12
	s_branch .LBB0_131
